# grid barrier: XCD members poll the top-level generation word directly (local barrier count), no per-XCD relay hop; on top of v018
# baseline (speedup 1.0000x reference)
_Z8mega_fwd4Args:
	s_mov_b32 s20, 0
	s_nop 1
	v_writelane_b32 v255, s20, 47
	s_mov_b32 s4, 0
	v_lshl_add_u32 v1, v0, 2, 0
	s_mov_b32 s57, s2
	s_mov_b32 s5, 1
	v_add_u32_e32 v1, 0x21800, v1
	s_mov_b64 s[6:7], 0
	v_mov_b32_e32 v2, 0
	s_mov_b32 s8, s4
	s_branch .LBB0_2

.LBB0_261:
	s_or_b64 exec, exec, s[12:13]
	v_cvt_f32_u32_e32 v5, v3
	s_waitcnt vmcnt(0)
	v_readfirstlane_b32 s2, v4
	v_sub_u32_e32 v4, 0, v3
	v_rcp_iflag_f32_e32 v5, v5
	v_add_u32_e32 v6, s2, v2
	v_mul_f32_e32 v5, 0x4f7ffffe, v5
	v_cvt_u32_f32_e32 v5, v5
	v_mul_lo_u32 v2, v4, v5
	v_mul_hi_u32 v2, v5, v2
	v_add_u32_e32 v2, v5, v2
	v_mul_hi_u32 v2, v6, v2
	v_mul_lo_u32 v4, v2, v3
	v_sub_u32_e32 v4, v6, v4
	v_add_u32_e32 v5, 1, v2
	v_cmp_ge_u32_e32 vcc, v4, v3
	s_nop 1
	v_cndmask_b32_e32 v2, v2, v5, vcc
	v_sub_u32_e32 v5, v4, v3
	v_cndmask_b32_e32 v4, v4, v5, vcc
	v_add_u32_e32 v5, 1, v2
	v_cmp_ge_u32_e32 vcc, v4, v3
	v_add_u32_e32 v4, 1, v6
	s_nop 0
	v_cndmask_b32_e32 v2, v2, v5, vcc
	v_mul_lo_u32 v5, v3, v2
	v_add_u32_e32 v3, v5, v3
	v_cmp_ne_u32_e32 vcc, v4, v3
	s_and_saveexec_b64 s[2:3], vcc
	s_xor_b64 s[10:11], exec, s[2:3]
	s_cbranch_execz .LBB0_275
	s_waitcnt lgkmcnt(0)
	v_readlane_b32 s16, v255, 47
	v_mov_b32_e32 v1, 0x7000
	global_load_dword v1, v1, s[6:7] offset:1280 sc1
	v_mov_b32_e32 v2, s16
	s_add_u32 s16, s6, 0x7500
	s_addc_u32 s17, s7, 0
	s_waitcnt vmcnt(0)
	v_cmp_eq_u32_e32 vcc, v1, v2
	s_and_saveexec_b64 s[12:13], vcc
	s_cbranch_execz .LBB0_274
	s_add_u32 s14, s6, 0x4200
	s_addc_u32 s15, s7, 0
	s_mov_b32 s2, 1
	s_mov_b64 s[18:19], 0
	v_mov_b32_e32 v1, 0
	s_branch .LBB0_265

.LBB0_295:
	s_or_b64 exec, exec, s[4:5]
	s_waitcnt lgkmcnt(0)
	s_barrier
	v_readlane_b32 s2, v255, 47
	s_nop 3
	s_add_i32 s2, s2, 1
	s_nop 1
	v_writelane_b32 v255, s2, 47

.LBB0_1652:
	s_or_b64 exec, exec, s[12:13]
	v_cvt_f32_u32_e32 v7, v5
	s_waitcnt vmcnt(0)
	v_readfirstlane_b32 s2, v6
	v_sub_u32_e32 v6, 0, v5
	v_rcp_iflag_f32_e32 v7, v7
	v_add_u32_e32 v8, s2, v2
	v_mul_f32_e32 v7, 0x4f7ffffe, v7
	v_cvt_u32_f32_e32 v7, v7
	v_mul_lo_u32 v2, v6, v7
	v_mul_hi_u32 v2, v7, v2
	v_add_u32_e32 v2, v7, v2
	v_mul_hi_u32 v2, v8, v2
	v_mul_lo_u32 v6, v2, v5
	v_sub_u32_e32 v6, v8, v6
	v_add_u32_e32 v7, 1, v2
	v_cmp_ge_u32_e32 vcc, v6, v5
	s_nop 1
	v_cndmask_b32_e32 v2, v2, v7, vcc
	v_sub_u32_e32 v7, v6, v5
	v_cndmask_b32_e32 v6, v6, v7, vcc
	v_add_u32_e32 v7, 1, v2
	v_cmp_ge_u32_e32 vcc, v6, v5
	v_add_u32_e32 v6, 1, v8
	s_nop 0
	v_cndmask_b32_e32 v2, v2, v7, vcc
	v_mul_lo_u32 v7, v5, v2
	v_add_u32_e32 v5, v7, v5
	v_cmp_ne_u32_e32 vcc, v6, v5
	s_and_saveexec_b64 s[2:3], vcc
	s_xor_b64 s[10:11], exec, s[2:3]
	s_cbranch_execz .LBB0_1669
	s_waitcnt lgkmcnt(0)
	v_readlane_b32 s16, v255, 47
	v_mov_b32_e32 v4, 0x7000
	global_load_dword v4, v4, s[6:7] offset:1280 sc1
	v_mov_b32_e32 v2, s16
	s_add_u32 s16, s6, 0x7500
	s_addc_u32 s17, s7, 0
	s_waitcnt vmcnt(0)
	v_cmp_eq_u32_e32 vcc, v4, v2
	s_and_saveexec_b64 s[12:13], vcc
	s_cbranch_execz .LBB0_1668
	s_add_u32 s14, s6, 0x4200
	s_addc_u32 s15, s7, 0
	s_mov_b32 s2, 1
	s_mov_b64 s[18:19], 0
	s_branch .LBB0_1656
